# seam 2 early counter read + L1 invalidate under PP store drain (with cached placement flag), on top of v23
# speedup vs baseline: 1.0052x; 1.0003x over previous
; __device__ __forceinline__ unsigned xb_ld(unsigned* p)              { return __hip_atomic_load(p, __ATOMIC_RELAXED, __HIP_MEMORY_SCOPE_AGENT); }
; #define XB_SPIN(cond, bar) do { unsigned _sp = 0; while (cond) { __builtin_amdgcn_s_sleep(1); \
;     if ((++_sp & 255u) == 0u) { if (xb_ld(&(bar)[XB_TMO])) break; if (_sp > XB_SPIN_CAP) { atomicAdd(&(bar)[XB_TMO], 1u); break; } } } } while (0)
; __device__ __forceinline__ bool xb_thread0(int wave) { return wave == 0 && hw_lane() == 0; }
; #define BOTH(k) (IN(k) && IN((k) + 1))
; #define GRID_BAR() xcd_barrier(bar)
; __global__ void __launch_bounds__(NWAVES * 64, 2) mk_fwd(Args args) {
;     ...
;         if (BOTH(5)) {
;             if (F.G == 256 && lo == 0 && hi == 7 && __hip_atomic_load((unsigned*)(F.ctl + CW_LB + 1024), RLX_AGENT) == 0u) {
;                 asm volatile("s_waitcnt vmcnt(0)" ::: "memory"); __syncthreads();
;                 if (xb_thread0(F.wave)) { unsigned* cnt_ = (unsigned*)(F.ctl + CW_LB + 2048 + 64 * (8 * (F.vcu >> 5) + (F.vcu & 7))); XB_SPIN(xb_ld(cnt_) < 8u, bar.bar);
;                     __builtin_amdgcn_fence(__ATOMIC_ACQUIRE, "agent"); asm volatile("s_waitcnt vmcnt(0)" ::: "memory"); }
;                 __syncthreads(); }
;             else GRID_BAR(); }
.LBB0_888:
	v_readlane_b32 s100, v252, 11
	v_readlane_b32 s101, v252, 12
	s_nop 3
	s_and_b64 vcc, exec, s[100:101]
	s_cbranch_vccz .Ls2e_skipA
	v_readlane_b32 s100, v252, 4
	v_mov_b32_e32 v254, 0x12000
	s_nop 3
	s_lshr_b32 s101, s100, 2
	s_and_b32 s101, s101, 0x3fffff8
	s_and_b32 s100, s100, 7
	s_or_b32 s100, s101, s100
	s_lshl_b32 s100, s100, 8
	s_add_u32 s98, s96, s100
	s_addc_u32 s99, s97, 0
	global_load_dword v254, v254, s[98:99] sc1

; __device__ __forceinline__ unsigned xb_ld(unsigned* p)              { return __hip_atomic_load(p, __ATOMIC_RELAXED, __HIP_MEMORY_SCOPE_AGENT); }
; #define XB_SPIN(cond, bar) do { unsigned _sp = 0; while (cond) { __builtin_amdgcn_s_sleep(1); \
;     if ((++_sp & 255u) == 0u) { if (xb_ld(&(bar)[XB_TMO])) break; if (_sp > XB_SPIN_CAP) { atomicAdd(&(bar)[XB_TMO], 1u); break; } } } } while (0)
; __device__ __forceinline__ bool xb_thread0(int wave) { return wave == 0 && hw_lane() == 0; }
; #define BOTH(k) (IN(k) && IN((k) + 1))
; #define GRID_BAR() xcd_barrier(bar)
; __global__ void __launch_bounds__(NWAVES * 64, 2) mk_fwd(Args args) {
;     ...
;         if (BOTH(5)) {
;             if (F.G == 256 && lo == 0 && hi == 7 && __hip_atomic_load((unsigned*)(F.ctl + CW_LB + 1024), RLX_AGENT) == 0u) {
;                 asm volatile("s_waitcnt vmcnt(0)" ::: "memory"); __syncthreads();
;                 if (xb_thread0(F.wave)) { unsigned* cnt_ = (unsigned*)(F.ctl + CW_LB + 2048 + 64 * (8 * (F.vcu >> 5) + (F.vcu & 7))); XB_SPIN(xb_ld(cnt_) < 8u, bar.bar);
;                     __builtin_amdgcn_fence(__ATOMIC_ACQUIRE, "agent"); asm volatile("s_waitcnt vmcnt(0)" ::: "memory"); }
;                 __syncthreads(); }
;             else GRID_BAR(); }
.Ls2e_noinv:
	v_mov_b32_e32 v255, 0x20000
	v_mov_b32_e32 v254, s98
	ds_write_b32 v255, v254
	s_waitcnt lgkmcnt(0)

; __device__ __forceinline__ unsigned xb_ld(unsigned* p)              { return __hip_atomic_load(p, __ATOMIC_RELAXED, __HIP_MEMORY_SCOPE_AGENT); }
; #define XB_SPIN(cond, bar) do { unsigned _sp = 0; while (cond) { __builtin_amdgcn_s_sleep(1); \
;     if ((++_sp & 255u) == 0u) { if (xb_ld(&(bar)[XB_TMO])) break; if (_sp > XB_SPIN_CAP) { atomicAdd(&(bar)[XB_TMO], 1u); break; } } } } while (0)
; __device__ __forceinline__ bool xb_thread0(int wave) { return wave == 0 && hw_lane() == 0; }
; #define BOTH(k) (IN(k) && IN((k) + 1))
; #define GRID_BAR() xcd_barrier(bar)
; __global__ void __launch_bounds__(NWAVES * 64, 2) mk_fwd(Args args) {
;     ...
;         if (BOTH(5)) {
;             if (F.G == 256 && lo == 0 && hi == 7 && __hip_atomic_load((unsigned*)(F.ctl + CW_LB + 1024), RLX_AGENT) == 0u) {
;                 asm volatile("s_waitcnt vmcnt(0)" ::: "memory"); __syncthreads();
;                 if (xb_thread0(F.wave)) { unsigned* cnt_ = (unsigned*)(F.ctl + CW_LB + 2048 + 64 * (8 * (F.vcu >> 5) + (F.vcu & 7))); XB_SPIN(xb_ld(cnt_) < 8u, bar.bar);
;                     __builtin_amdgcn_fence(__ATOMIC_ACQUIRE, "agent"); asm volatile("s_waitcnt vmcnt(0)" ::: "memory"); }
;                 __syncthreads(); }
;             else GRID_BAR(); }
.LBB0_889:
	s_and_b64 vcc, exec, s[2:3]
	s_cbranch_vccz .Ls2e_slow
	v_mov_b32_e32 v255, 0x20000
	ds_read_b32 v255, v255
	s_waitcnt lgkmcnt(0)
	v_readfirstlane_b32 s98, v255
	s_nop 3
	s_cmp_eq_u32 s98, 1
	s_cbranch_scc1 .LBB0_967

; __global__ void __launch_bounds__(NWAVES * 64, 2) mk_fwd(Args args) {
	.amdhsa_kernel _Z6mk_fwd4Args
		.amdhsa_group_segment_fixed_size 0
		.amdhsa_private_segment_fixed_size 0
		.amdhsa_kernarg_size 440
		.amdhsa_user_sgpr_count 2
		.amdhsa_user_sgpr_dispatch_ptr 0
		.amdhsa_user_sgpr_queue_ptr 0
		.amdhsa_user_sgpr_kernarg_segment_ptr 1
		.amdhsa_user_sgpr_dispatch_id 0
		.amdhsa_user_sgpr_kernarg_preload_length 0
		.amdhsa_user_sgpr_kernarg_preload_offset 0
		.amdhsa_user_sgpr_private_segment_size 0
		.amdhsa_uses_dynamic_stack 0
		.amdhsa_enable_private_segment 0
		.amdhsa_system_sgpr_workgroup_id_x 1
		.amdhsa_system_sgpr_workgroup_id_y 0
		.amdhsa_system_sgpr_workgroup_id_z 0
		.amdhsa_system_sgpr_workgroup_info 0
		.amdhsa_system_vgpr_workitem_id 0
		.amdhsa_next_free_vgpr 256
		.amdhsa_next_free_sgpr 102
		.amdhsa_accum_offset 256
		.amdhsa_reserve_vcc 1
		.amdhsa_float_round_mode_32 0
		.amdhsa_float_round_mode_16_64 0
		.amdhsa_float_denorm_mode_32 3
		.amdhsa_float_denorm_mode_16_64 3
		.amdhsa_dx10_clamp 1
		.amdhsa_ieee_mode 1
		.amdhsa_fp16_overflow 0
		.amdhsa_tg_split 0
		.amdhsa_exception_fp_ieee_invalid_op 0
		.amdhsa_exception_fp_denorm_src 0
		.amdhsa_exception_fp_ieee_div_zero 0
		.amdhsa_exception_fp_ieee_overflow 0
		.amdhsa_exception_fp_ieee_underflow 0
		.amdhsa_exception_fp_ieee_inexact 0
		.amdhsa_exception_int_div_zero 0
	.end_amdhsa_kernel

; __global__ void __launch_bounds__(NWAVES * 64, 2) mk_fwd(Args args) {
.Lfunc_end0:
	.size	_Z6mk_fwd4Args, .Lfunc_end0-_Z6mk_fwd4Args
	.set _Z6mk_fwd4Args.num_vgpr, 256
	.set _Z6mk_fwd4Args.num_agpr, 0
	.set _Z6mk_fwd4Args.numbered_sgpr, 102
	.set _Z6mk_fwd4Args.num_named_barrier, 0
	.set _Z6mk_fwd4Args.private_seg_size, 0
	.set _Z6mk_fwd4Args.uses_vcc, 1
	.set _Z6mk_fwd4Args.uses_flat_scratch, 0
	.set _Z6mk_fwd4Args.has_dyn_sized_stack, 0
	.set _Z6mk_fwd4Args.has_recursion, 0
	.set _Z6mk_fwd4Args.has_indirect_call, 0

; __global__ void __launch_bounds__(NWAVES * 64, 2) mk_fwd(Args args) {
amdhsa.kernels:
  - .agpr_count:     0
    .args:
      - .offset:         0
        .size:           184
        .value_kind:     by_value
      - .offset:         184
        .size:           4
        .value_kind:     hidden_block_count_x
      - .offset:         188
        .size:           4
        .value_kind:     hidden_block_count_y
      - .offset:         192
        .size:           4
        .value_kind:     hidden_block_count_z
      - .offset:         196
        .size:           2
        .value_kind:     hidden_group_size_x
      - .offset:         198
        .size:           2
        .value_kind:     hidden_group_size_y
      - .offset:         200
        .size:           2
        .value_kind:     hidden_group_size_z
      - .offset:         202
        .size:           2
        .value_kind:     hidden_remainder_x
      - .offset:         204
        .size:           2
        .value_kind:     hidden_remainder_y
      - .offset:         206
        .size:           2
        .value_kind:     hidden_remainder_z
      - .offset:         224
        .size:           8
        .value_kind:     hidden_global_offset_x
      - .offset:         232
        .size:           8
        .value_kind:     hidden_global_offset_y
      - .offset:         240
        .size:           8
        .value_kind:     hidden_global_offset_z
      - .offset:         248
        .size:           2
        .value_kind:     hidden_grid_dims
      - .offset:         304
        .size:           4
        .value_kind:     hidden_dynamic_lds_size
    .group_segment_fixed_size: 0
    .kernarg_segment_align: 8
    .kernarg_segment_size: 440
    .language:       OpenCL C
    .language_version:
      - 2
      - 0
    .max_flat_workgroup_size: 512
    .name:           _Z6mk_fwd4Args
    .private_segment_fixed_size: 0
    .sgpr_count:     108
    .sgpr_spill_count: 51
    .symbol:         _Z6mk_fwd4Args.kd
    .uniform_work_group_size: 1
    .uses_dynamic_stack: false
    .vgpr_count:     256
    .vgpr_spill_count: 0
    .wavefront_size: 64
